# fused final-norm rendezvous: no L2 write-back before the arrival atomic (only memory-side f32 atomics are published) and no L1 invalidate per poll (sums are read with sc1 loads)
# baseline (speedup 1.0000x reference)
; __device__ __forceinline__ int tid_opq() { int t = threadIdx.x; asm volatile("" : "+v"(t)); return t; }
;     __device__ __forceinline__ void operator()(const f32x4 (&acc_)[2][2][4][2], const Unit& u, int wr, int wc, int fr, int fq, const float (&)[8]) const {
;     ...
;         for (int ai = 0; ai < 2; ++ai) { const float v = fq == 0 ? ssv[ai][0] : fq == 1 ? ssv[ai][1] : fq == 2 ? ssv[ai][2] : ssv[ai][3];
;             (void)__hip_atomic_fetch_add(RS + row0 + ai * 128 + fq * 16, v, __ATOMIC_RELAXED, __HIP_MEMORY_SCOPE_AGENT); }
;         asm volatile("s_waitcnt vmcnt(0)" ::: "memory");
;         __syncthreads();
;         if (tid_opq() == 0) {
;             (void)__hip_atomic_fetch_add(cnt + u.pm * 16, 1u, __ATOMIC_RELEASE, __HIP_MEMORY_SCOPE_AGENT);
;             unsigned spins = 0;
;             while (__hip_atomic_load(cnt + u.pm * 16, __ATOMIC_ACQUIRE, __HIP_MEMORY_SCOPE_AGENT) < 4u && ++spins < (1u << 22)) __builtin_amdgcn_s_sleep(1);
.LBB0_439:
	s_or_b64 exec, exec, s[16:17]
	global_atomic_add_f32 v[130:131], v132, off offset:512
	s_waitcnt vmcnt(0)
	v_mov_b32_e32 v130, v187
	s_waitcnt vmcnt(0)
	s_barrier
	s_nop 0
	v_cmp_eq_u32_e32 vcc, 0, v130
	s_and_saveexec_b64 s[16:17], vcc
	s_cbranch_execz .LBB0_453
	s_lshl_b32 s14, s87, 4
	s_mov_b64 s[30:31], exec
	s_ashr_i32 s15, s14, 31
	s_lshl_b64 s[14:15], s[14:15], 2
	v_readlane_b32 s3, v250, 49
	v_mbcnt_lo_u32_b32 v130, s30, 0
	s_add_u32 s18, s3, s14
	v_readlane_b32 s3, v250, 50
	v_mbcnt_hi_u32_b32 v130, s31, v130
	s_addc_u32 s19, s3, s15
	v_cmp_eq_u32_e32 vcc, 0, v130
	s_and_saveexec_b64 s[72:73], vcc
	s_cbranch_execz .LBB0_442
	s_bcnt1_i32_b64 s3, s[30:31]
	v_mov_b32_e32 v130, s3
	global_atomic_add v1, v130, s[18:19]
.LBB0_442:
	s_or_b64 exec, exec, s[72:73]
	global_load_dword v130, v1, s[18:19] sc1
	s_waitcnt vmcnt(0)
	v_cmp_lt_u32_e32 vcc, 3, v130
	s_cbranch_vccnz .LBB0_453
	s_mov_b32 s3, 0x3ffff8
	s_branch .LBB0_445

;     __device__ __forceinline__ void operator()(const f32x4 (&acc_)[2][2][4][2], const Unit& u, int wr, int wc, int fr, int fq, const float (&)[8]) const {
;     ...
;             while (__hip_atomic_load(cnt + u.pm * 16, __ATOMIC_ACQUIRE, __HIP_MEMORY_SCOPE_AGENT) < 4u && ++spins < (1u << 22)) __builtin_amdgcn_s_sleep(1);
.LBB0_445:
	s_sleep 1
	global_load_dword v130, v1, s[18:19] sc1
	s_waitcnt vmcnt(0)
	s_mov_b64 s[30:31], -1
	v_cmp_lt_u32_e32 vcc, 3, v130
	s_cbranch_vccnz .LBB0_444
	s_sleep 1
	global_load_dword v130, v1, s[18:19] sc1
	s_waitcnt vmcnt(0)
	v_cmp_gt_u32_e32 vcc, 4, v130
	s_cbranch_vccz .LBB0_444
	s_sleep 1
	global_load_dword v130, v1, s[18:19] sc1
	s_waitcnt vmcnt(0)
	v_cmp_gt_u32_e32 vcc, 4, v130
	s_cbranch_vccz .LBB0_444
	s_sleep 1
	global_load_dword v130, v1, s[18:19] sc1
	s_waitcnt vmcnt(0)
	v_cmp_gt_u32_e32 vcc, 4, v130
	s_cbranch_vccz .LBB0_444
	s_sleep 1
	global_load_dword v130, v1, s[18:19] sc1
	s_waitcnt vmcnt(0)
	v_cmp_gt_u32_e32 vcc, 4, v130
	s_cbranch_vccz .LBB0_444
	s_sleep 1
	global_load_dword v130, v1, s[18:19] sc1
	s_waitcnt vmcnt(0)
	v_cmp_gt_u32_e32 vcc, 4, v130
	s_cbranch_vccz .LBB0_444
	s_sleep 1
	global_load_dword v130, v1, s[18:19] sc1
	s_waitcnt vmcnt(0)
	s_cmp_eq_u32 s3, 0
	s_cselect_b64 s[14:15], -1, 0
	v_cmp_lt_u32_e32 vcc, 3, v130
	s_or_b64 s[14:15], vcc, s[14:15]
	s_andn2_b64 vcc, exec, s[14:15]
	s_cbranch_vccz .LBB0_444
	s_sleep 1
	global_load_dword v130, v1, s[18:19] sc1
	s_waitcnt vmcnt(0)
	s_add_i32 s3, s3, -8
	v_cmp_lt_u32_e64 s[30:31], 3, v130
	s_branch .LBB0_444
